# MoE gate/up L0 k-loop: next-step global loads interleaved into the MFMA stream (1 per 4 MFMA) instead of a pre-barrier burst
# baseline (speedup 1.0000x reference)
.LBB0_1186:
	s_waitcnt vmcnt(1)
	v_cvt_pk_bf16_f32 v226, v176, v160
	s_waitcnt vmcnt(4)
	v_cvt_pk_bf16_f32 v227, v164, v168
	s_waitcnt vmcnt(2)
	v_cvt_pk_bf16_f32 v228, v172, v180
	s_waitcnt vmcnt(0)
	v_cvt_pk_bf16_f32 v229, v184, v188
	s_cmpk_gt_u32 s5, 0x3bf
	ds_write_b128 v192, v[120:123]
	ds_write_b128 v192, v[124:127] offset:4096
	ds_write_b128 v192, v[128:131] offset:8192
	ds_write_b128 v192, v[132:135] offset:12288
	ds_write_b128 v192, v[136:139] offset:16384
	ds_write_b128 v192, v[140:143] offset:20480
	ds_write_b128 v192, v[144:147] offset:24576
	ds_write_b128 v192, v[152:155] offset:28672
	ds_write_b128 v223, v[226:229] offset:32768
	v_cvt_pk_bf16_f32 v226, v177, v161
	v_cvt_pk_bf16_f32 v227, v165, v169
	v_cvt_pk_bf16_f32 v228, v173, v181
	v_cvt_pk_bf16_f32 v229, v185, v189
	s_cselect_b64 s[2:3], -1, 0
	ds_write_b128 v223, v[226:229] offset:32896
	v_cvt_pk_bf16_f32 v226, v178, v162
	v_cvt_pk_bf16_f32 v227, v166, v170
	v_cvt_pk_bf16_f32 v228, v174, v182
	v_cvt_pk_bf16_f32 v229, v186, v190
	ds_write_b128 v224, v[226:229] offset:32768
	v_cvt_pk_bf16_f32 v226, v179, v163
	v_cvt_pk_bf16_f32 v227, v167, v171
	v_cvt_pk_bf16_f32 v228, v175, v183
	v_cvt_pk_bf16_f32 v229, v187, v191
	s_and_b64 vcc, exec, s[2:3]
	ds_write_b128 v225, v[226:229] offset:32768
	s_cbranch_vccnz .LBB0_1185
	v_add_co_u32_e32 v160, vcc, s14, v212
	v_lshl_add_u64 v[120:121], v[194:195], 0, v[196:197]
	s_nop 0
	v_addc_co_u32_e32 v161, vcc, 0, v213, vcc
	v_add_co_u32_e32 v164, vcc, s15, v212
	v_lshl_add_u64 v[124:125], v[194:195], 0, v[198:199]
	s_nop 0
	v_addc_co_u32_e32 v165, vcc, 0, v213, vcc
	v_add_co_u32_e32 v168, vcc, s16, v212
	v_lshl_add_u64 v[128:129], v[194:195], 0, v[200:201]
	s_nop 0
	v_addc_co_u32_e32 v169, vcc, 0, v213, vcc
	v_add_co_u32_e32 v172, vcc, 0x8000, v212
	v_lshl_add_u64 v[132:133], v[194:195], 0, v[202:203]
	s_nop 0
	v_addc_co_u32_e32 v173, vcc, 0, v213, vcc
	v_add_co_u32_e32 v176, vcc, 0xa000, v212
	v_lshl_add_u64 v[136:137], v[194:195], 0, v[204:205]
	s_nop 0
	v_addc_co_u32_e32 v177, vcc, 0, v213, vcc
	v_add_co_u32_e32 v178, vcc, 0xc000, v212
	v_lshl_add_u64 v[140:141], v[194:195], 0, v[206:207]
	s_nop 0
	v_addc_co_u32_e32 v179, vcc, 0, v213, vcc
	v_add_co_u32_e32 v188, vcc, 0xe000, v212
	v_lshl_add_u64 v[144:145], v[194:195], 0, v[208:209]
	v_lshl_add_u64 v[152:153], v[194:195], 0, v[210:211]
	v_addc_co_u32_e32 v189, vcc, 0, v213, vcc
	s_nop 0
	s_nop 0
	s_nop 0
	s_nop 0
	s_nop 0
	s_nop 0
	s_nop 0
	s_nop 0
	s_nop 0
	s_nop 0
	s_nop 0
	s_nop 0
	s_nop 0
	s_nop 0
	s_add_i32 s5, s5, 64
	s_waitcnt lgkmcnt(0)
	s_barrier
	s_setprio 1
	ds_read_b128 v[226:229], v220
	ds_read_b128 v[246:249], v220 offset:2048
	ds_read_b128 v[230:233], v219 offset:32768
	ds_read_b128 v[234:237], v219 offset:34816
	ds_read_b128 v[238:241], v219 offset:36864
	ds_read_b128 v[242:245], v219 offset:38912
	ds_read_b128 v[214:217], v220 offset:4096
	s_waitcnt lgkmcnt(4)
	v_mfma_f32_16x16x32_bf16 v[156:159], v[226:229], v[230:233], v[156:159]
	s_waitcnt lgkmcnt(3)
	v_mfma_f32_16x16x32_bf16 v[116:119], v[226:229], v[234:237], v[116:119]
	s_waitcnt lgkmcnt(2)
	v_mfma_f32_16x16x32_bf16 v[148:151], v[226:229], v[238:241], v[148:151]
	s_waitcnt lgkmcnt(1)
	v_mfma_f32_16x16x32_bf16 v[112:115], v[226:229], v[242:245], v[112:115]
	global_load_dwordx4 v[120:123], v[120:121], off
	ds_read_b128 v[226:229], v220 offset:6144
	v_mfma_f32_16x16x32_bf16 v[108:111], v[246:249], v[230:233], v[108:111]
	v_mfma_f32_16x16x32_bf16 v[100:103], v[246:249], v[234:237], v[100:103]
	v_mfma_f32_16x16x32_bf16 v[104:107], v[246:249], v[238:241], v[104:107]
	v_mfma_f32_16x16x32_bf16 v[96:99], v[246:249], v[242:245], v[96:99]
	global_load_dwordx4 v[124:127], v[124:125], off
	ds_read_b128 v[246:249], v220 offset:8192
	s_waitcnt lgkmcnt(2)
	v_mfma_f32_16x16x32_bf16 v[92:95], v[214:217], v[230:233], v[92:95]
	v_mfma_f32_16x16x32_bf16 v[84:87], v[214:217], v[234:237], v[84:87]
	v_mfma_f32_16x16x32_bf16 v[88:91], v[214:217], v[238:241], v[88:91]
	v_mfma_f32_16x16x32_bf16 v[80:83], v[214:217], v[242:245], v[80:83]
	global_load_dwordx4 v[128:131], v[128:129], off
	ds_read_b128 v[214:217], v220 offset:10240
	s_waitcnt lgkmcnt(2)
	v_mfma_f32_16x16x32_bf16 v[76:79], v[226:229], v[230:233], v[76:79]
	v_mfma_f32_16x16x32_bf16 v[68:71], v[226:229], v[234:237], v[68:71]
	v_mfma_f32_16x16x32_bf16 v[72:75], v[226:229], v[238:241], v[72:75]
	v_mfma_f32_16x16x32_bf16 v[64:67], v[226:229], v[242:245], v[64:67]
	global_load_dwordx4 v[132:135], v[132:133], off
	ds_read_b128 v[226:229], v220 offset:12288
	s_waitcnt lgkmcnt(2)
	v_mfma_f32_16x16x32_bf16 v[60:63], v[246:249], v[230:233], v[60:63]
	v_mfma_f32_16x16x32_bf16 v[52:55], v[246:249], v[234:237], v[52:55]
	v_mfma_f32_16x16x32_bf16 v[56:59], v[246:249], v[238:241], v[56:59]
	v_mfma_f32_16x16x32_bf16 v[48:51], v[246:249], v[242:245], v[48:51]
	global_load_dwordx4 v[136:139], v[136:137], off
	ds_read_b128 v[246:249], v220 offset:14336
	s_waitcnt lgkmcnt(2)
	v_mfma_f32_16x16x32_bf16 v[44:47], v[214:217], v[230:233], v[44:47]
	v_mfma_f32_16x16x32_bf16 v[36:39], v[214:217], v[234:237], v[36:39]
	v_mfma_f32_16x16x32_bf16 v[40:43], v[214:217], v[238:241], v[40:43]
	v_mfma_f32_16x16x32_bf16 v[32:35], v[214:217], v[242:245], v[32:35]
	global_load_dwordx4 v[140:143], v[140:141], off
	s_waitcnt lgkmcnt(1)
	v_mfma_f32_16x16x32_bf16 v[24:27], v[226:229], v[230:233], v[24:27]
	v_mfma_f32_16x16x32_bf16 v[16:19], v[226:229], v[234:237], v[16:19]
	v_mfma_f32_16x16x32_bf16 v[28:31], v[226:229], v[238:241], v[28:31]
	v_mfma_f32_16x16x32_bf16 v[20:23], v[226:229], v[242:245], v[20:23]
	global_load_dwordx4 v[144:147], v[144:145], off
	s_waitcnt lgkmcnt(0)
	v_mfma_f32_16x16x32_bf16 v[8:11], v[246:249], v[230:233], v[8:11]
	v_mfma_f32_16x16x32_bf16 v[0:3], v[246:249], v[234:237], v[0:3]
	v_mfma_f32_16x16x32_bf16 v[12:15], v[246:249], v[238:241], v[12:15]
	v_mfma_f32_16x16x32_bf16 v[4:7], v[246:249], v[242:245], v[4:7]
	global_load_dwordx4 v[152:155], v[152:153], off
	ds_read_b128 v[214:217], v222
	ds_read_b128 v[242:245], v222 offset:2048
	ds_read_b128 v[226:229], v221 offset:32768
	ds_read_b128 v[230:233], v221 offset:34816
	ds_read_b128 v[234:237], v221 offset:36864
	ds_read_b128 v[238:241], v221 offset:38912
	ds_read_b128 v[246:249], v222 offset:4096
	s_waitcnt lgkmcnt(4)
	v_mfma_f32_16x16x32_bf16 v[156:159], v[214:217], v[226:229], v[156:159]
	s_waitcnt lgkmcnt(3)
	v_mfma_f32_16x16x32_bf16 v[116:119], v[214:217], v[230:233], v[116:119]
	s_waitcnt lgkmcnt(2)
	v_mfma_f32_16x16x32_bf16 v[148:151], v[214:217], v[234:237], v[148:151]
	s_waitcnt lgkmcnt(1)
	v_mfma_f32_16x16x32_bf16 v[112:115], v[214:217], v[238:241], v[112:115]
	global_load_dwordx4 v[160:163], v[160:161], off
	ds_read_b128 v[214:217], v222 offset:6144
	v_mfma_f32_16x16x32_bf16 v[108:111], v[242:245], v[226:229], v[108:111]
	v_mfma_f32_16x16x32_bf16 v[100:103], v[242:245], v[230:233], v[100:103]
	v_mfma_f32_16x16x32_bf16 v[104:107], v[242:245], v[234:237], v[104:107]
	v_mfma_f32_16x16x32_bf16 v[96:99], v[242:245], v[238:241], v[96:99]
	global_load_dwordx4 v[164:167], v[164:165], off
	ds_read_b128 v[242:245], v222 offset:8192
	s_waitcnt lgkmcnt(2)
	v_mfma_f32_16x16x32_bf16 v[92:95], v[246:249], v[226:229], v[92:95]
	v_mfma_f32_16x16x32_bf16 v[84:87], v[246:249], v[230:233], v[84:87]
	v_mfma_f32_16x16x32_bf16 v[88:91], v[246:249], v[234:237], v[88:91]
	v_mfma_f32_16x16x32_bf16 v[80:83], v[246:249], v[238:241], v[80:83]
	global_load_dwordx4 v[168:171], v[168:169], off
	ds_read_b128 v[246:249], v222 offset:10240
	s_waitcnt lgkmcnt(2)
	v_mfma_f32_16x16x32_bf16 v[76:79], v[214:217], v[226:229], v[76:79]
	v_mfma_f32_16x16x32_bf16 v[68:71], v[214:217], v[230:233], v[68:71]
	v_mfma_f32_16x16x32_bf16 v[72:75], v[214:217], v[234:237], v[72:75]
	v_mfma_f32_16x16x32_bf16 v[64:67], v[214:217], v[238:241], v[64:67]
	global_load_dwordx4 v[172:175], v[172:173], off
	ds_read_b128 v[214:217], v222 offset:12288
	s_waitcnt lgkmcnt(2)
	v_mfma_f32_16x16x32_bf16 v[60:63], v[242:245], v[226:229], v[60:63]
	v_mfma_f32_16x16x32_bf16 v[52:55], v[242:245], v[230:233], v[52:55]
	v_mfma_f32_16x16x32_bf16 v[56:59], v[242:245], v[234:237], v[56:59]
	v_mfma_f32_16x16x32_bf16 v[48:51], v[242:245], v[238:241], v[48:51]
	global_load_dwordx4 v[180:183], v[176:177], off
	ds_read_b128 v[242:245], v222 offset:14336
	s_waitcnt lgkmcnt(2)
	v_mfma_f32_16x16x32_bf16 v[44:47], v[246:249], v[226:229], v[44:47]
	v_mfma_f32_16x16x32_bf16 v[36:39], v[246:249], v[230:233], v[36:39]
	v_mfma_f32_16x16x32_bf16 v[40:43], v[246:249], v[234:237], v[40:43]
	v_mfma_f32_16x16x32_bf16 v[32:35], v[246:249], v[238:241], v[32:35]
	global_load_dwordx4 v[184:187], v[178:179], off
	s_waitcnt lgkmcnt(1)
	v_mfma_f32_16x16x32_bf16 v[24:27], v[214:217], v[226:229], v[24:27]
	v_mfma_f32_16x16x32_bf16 v[16:19], v[214:217], v[230:233], v[16:19]
	v_mfma_f32_16x16x32_bf16 v[28:31], v[214:217], v[234:237], v[28:31]
	v_mfma_f32_16x16x32_bf16 v[20:23], v[214:217], v[238:241], v[20:23]
	global_load_dwordx4 v[176:179], v[212:213], off
	s_waitcnt lgkmcnt(0)
	v_mfma_f32_16x16x32_bf16 v[8:11], v[242:245], v[226:229], v[8:11]
	v_mfma_f32_16x16x32_bf16 v[0:3], v[242:245], v[230:233], v[0:3]
	v_mfma_f32_16x16x32_bf16 v[12:15], v[242:245], v[234:237], v[12:15]
	v_mfma_f32_16x16x32_bf16 v[4:7], v[242:245], v[238:241], v[4:7]
	global_load_dwordx4 v[188:191], v[188:189], off
	s_setprio 0
	s_mov_b64 s[10:11], 0x80
	s_andn2_b64 vcc, exec, s[2:3]
	s_mov_b64 s[2:3], 0x80000
	v_lshl_add_u64 v[194:195], v[194:195], 0, s[10:11]
	v_lshl_add_u64 v[212:213], v[212:213], 0, s[2:3]
	s_barrier
	s_cbranch_vccz .LBB0_1183
	s_branch .LBB0_1186
